# P6: ready6 acquire issued by wave 0 before the last unit's epilogue stores; loop drain waits vmcnt(16) (loads only), so the sample GEMM does not wait for the poll or the store acks
# baseline (speedup 1.0000x reference)
; __device__ __forceinline__ int fresh_tid() { int t = threadIdx.x; asm volatile("" : "+v"(t)); return t; }
;     const int tid = fresh_tid(), lane = tid & 63, gw = blockIdx.x * 8 + (tid >> 6), nw = (nblk ? nblk : (int)gridDim.x) * 8;
;     const float* mod = (const float*)(p.ws + WS_MOD); bf16_t* H = (bf16_t*)(p.ws + WS_H);
;     f32x4 gv[4];
; #pragma unroll
;     for (int i = 0; i < 4; ++i) gv[i] = *(const f32x4*)(g + (i >> 1) * 512 + lane * 8 + (i & 1) * 4);
;     for (int rowb = r0 + gw; rowb < r1; rowb += 4 * nw) {
; __global__ __launch_bounds__(512, 2) void fwd_megakernel(Params p) {
;     ...
;     { unsigned* ready6 = (unsigned*)(p.ws + WS_CNT) + CNT_READY6 * 64;
;     ...
;       if (bid < 16) {
;           rownorm_phase<false, true>(p, p.g_ffn, 3072, 4096, true, NP, NTOK, 16);
.Lgb_ret_4:
.LBB0_633:
	s_or_b64 exec, exec, s[0:1]
	v_mov_b32_e32 v242, 0
	s_add_u32 s24, s58, 0xc944000
	s_addc_u32 s25, s59, 0
	s_cmp_lt_i32 s2, 16
	s_cselect_b64 s[20:21], -1, 0
	s_and_b64 vcc, exec, s[20:21]
	s_waitcnt lgkmcnt(0)
	s_barrier
	s_cbranch_vccz .LBB0_653
	v_mov_b32_e32 v17, v224
	s_movk_i32 s0, 0x4080
	v_ashrrev_i32_e32 v18, 6, v17
	v_add_u32_e32 v16, s97, v18
	v_cmp_gt_i32_e32 vcc, s0, v16
	s_and_saveexec_b64 s[36:37], vcc
	s_cbranch_execz .LBB0_649
	v_lshlrev_b32_e32 v0, 3, v17
	v_and_b32_e32 v64, 0x1f8, v0
	v_lshlrev_b32_e32 v19, 2, v64
	global_load_dwordx4 v[0:3], v19, s[28:29] offset:16
	global_load_dwordx4 v[4:7], v19, s[28:29]
	global_load_dwordx4 v[8:11], v19, s[28:29] offset:2064
	global_load_dwordx4 v[12:15], v19, s[28:29] offset:2048
	v_and_b32_e32 v17, 63, v17
	v_lshlrev_b32_e32 v68, 5, v17
	v_ashrrev_i32_e32 v17, 31, v16
	v_add_u32_e32 v21, s95, v18
	v_lshlrev_b64 v[18:19], 12, v[16:17]
	v_lshl_add_u64 v[70:71], s[56:57], 0, v[18:19]
	v_add_u32_e32 v18, 0x4180, v21
	s_mov_b64 s[0:1], 0x1a70000
	v_lshlrev_b64 v[16:17], 11, v[16:17]
	v_ashrrev_i32_e32 v19, 31, v18
	v_and_b32_e32 v76, 15, v21
	v_lshlrev_b32_e32 v76, 4, v76
	v_and_b32_e32 v77, -16, v21
	v_lshl_add_u32 v76, v77, 11, v76
	v_mul_u32_u24_e32 v77, 30, v64
	v_add_u32_e32 v76, v76, v77
	v_add_u32_e32 v76, 0x3a70000, v76
	v_mov_b32_e32 v77, 0
	v_add_u32_e32 v16, 0x4100, v21
	v_lshlrev_b64 v[22:23], 12, v[18:19]
	v_lshlrev_b64 v[18:19], 11, v[18:19]
	v_ashrrev_i32_e32 v17, 31, v16
	v_lshl_add_u64 v[74:75], v[18:19], 0, s[0:1]
	v_lshlrev_b64 v[18:19], 12, v[16:17]
	v_lshlrev_b64 v[16:17], 11, v[16:17]
	v_lshl_add_u64 v[80:81], v[16:17], 0, s[0:1]
	v_add_u32_e32 v16, 0x4080, v21
	v_ashrrev_i32_e32 v17, 31, v16
	v_mov_b32_e32 v67, 0
	v_or_b32_e32 v20, 0x200, v64
	v_lshl_add_u64 v[78:79], s[56:57], 0, v[18:19]
	v_lshlrev_b64 v[18:19], 12, v[16:17]
	v_lshlrev_b64 v[16:17], 11, v[16:17]
	v_add_u32_e32 v89, 0x3e00, v21
	v_mov_b32_e32 v69, v67
	v_lshl_add_u64 v[72:73], s[56:57], 0, v[22:23]
	v_lshl_add_u64 v[82:83], s[56:57], 0, v[18:19]
	v_lshl_add_u64 v[84:85], v[16:17], 0, s[0:1]
	s_mov_b64 s[28:29], 0
	s_movk_i32 s12, 0x4000
	s_movk_i32 s13, 0x3f80
	s_movk_i32 s33, 0x3f00
	s_mov_b32 s38, 0x3a800000
	s_mov_b32 s39, 0x800000
	s_movk_i32 s60, 0x6000
	s_mov_b64 s[44:45], 0x4000
	s_mov_b64 s[46:47], 0x3000
	s_mov_b64 s[48:49], 0x400
	v_lshlrev_b32_e32 v86, 2, v20
	v_mov_b32_e32 v88, 0x358637bd
	s_movk_i32 s61, 0x3e80
	s_mov_b64 s[50:51], 0x200000
	s_movk_i32 s64, 0x3e7f
	s_mov_b64 s[52:53], s[58:59]
	s_branch .LBB0_637

; __device__ __forceinline__ int fresh_tid() { int t = threadIdx.x; asm volatile("" : "+v"(t)); return t; }
; __device__ __forceinline__ void spin_until(unsigned* p, unsigned need) { unsigned sp = 0; while (xb_ld(p) < need) { __builtin_amdgcn_s_sleep(1); if (++sp > (1u << 20)) break; } }
; __global__ __launch_bounds__(512, 2) void fwd_megakernel(Params p) {
;     ...
;       if (fresh_tid() == 0) { spin_until(ready6, 16u); __builtin_amdgcn_fence(__ATOMIC_ACQUIRE, "agent"); asm volatile("s_waitcnt vmcnt(0)" ::: "memory"); }
.Lp6_last:
	v_readfirstlane_b32 s86, v224
	s_cmp_gt_u32 s86, 63
	s_cbranch_scc1 .Lp6_nopoll
	v_mov_b32_e32 v241, 0
	global_load_dword v242, v241, s[24:25] sc1
	buffer_inv sc1

; #define PG8_WAIT_V(n) asm volatile("s_waitcnt vmcnt(" #n ")" ::: "memory")
; #define PG8_BAR __builtin_amdgcn_s_barrier()
; template <class Epi>
; __device__ __forceinline__ void gemm_phase(LAS unsigned char* lds, const Gemm g, const StaticOrder& S, const Epi& E, float* smem = nullptr) {
;     ...
;     PG8_WAIT_V(0);
;     if (wr == 0) PG8_BAR;
;     PG8_BAR;
.Lp6_exit:
	s_waitcnt vmcnt(16)
	s_cmpk_gt_u32 s12, 0xff
	s_cbranch_scc1 .LBB0_672
	s_barrier

; __device__ __forceinline__ int fresh_tid() { int t = threadIdx.x; asm volatile("" : "+v"(t)); return t; }
; __device__ __forceinline__ void spin_until(unsigned* p, unsigned need) { unsigned sp = 0; while (xb_ld(p) < need) { __builtin_amdgcn_s_sleep(1); if (++sp > (1u << 20)) break; } }
; __global__ __launch_bounds__(512, 2) void fwd_megakernel(Params p) {
;     ...
;       if (fresh_tid() == 0) { spin_until(ready6, 16u); __builtin_amdgcn_fence(__ATOMIC_ACQUIRE, "agent"); asm volatile("s_waitcnt vmcnt(0)" ::: "memory"); }
.LBB0_673:
	v_mov_b32_e32 v0, v224
	s_nop 0
	v_cmp_eq_u32_e32 vcc, 0, v0
	s_and_saveexec_b64 s[0:1], vcc
	s_cbranch_execz .LBB0_688
	v_cmp_lt_u32_e32 vcc, 15, v242
	s_cbranch_vccnz .LBB0_688
	s_mov_b32 s6, 0x100000
	v_mov_b32_e32 v0, 0
	s_branch .LBB0_677

; __global__ __launch_bounds__(512, 2) void fwd_megakernel(Params p) {
	.amdhsa_kernel _Z14fwd_megakernel6Params
		.amdhsa_group_segment_fixed_size 16
		.amdhsa_private_segment_fixed_size 0
		.amdhsa_kernarg_size 424
		.amdhsa_user_sgpr_count 2
		.amdhsa_user_sgpr_dispatch_ptr 0
		.amdhsa_user_sgpr_queue_ptr 0
		.amdhsa_user_sgpr_kernarg_segment_ptr 1
		.amdhsa_user_sgpr_dispatch_id 0
		.amdhsa_user_sgpr_kernarg_preload_length 0
		.amdhsa_user_sgpr_kernarg_preload_offset 0
		.amdhsa_user_sgpr_private_segment_size 0
		.amdhsa_uses_dynamic_stack 0
		.amdhsa_enable_private_segment 0
		.amdhsa_system_sgpr_workgroup_id_x 1
		.amdhsa_system_sgpr_workgroup_id_y 0
		.amdhsa_system_sgpr_workgroup_id_z 0
		.amdhsa_system_sgpr_workgroup_info 0
		.amdhsa_system_vgpr_workitem_id 2
		.amdhsa_next_free_vgpr 244
		.amdhsa_next_free_sgpr 102
		.amdhsa_accum_offset 244
		.amdhsa_reserve_vcc 1
		.amdhsa_float_round_mode_32 0
		.amdhsa_float_round_mode_16_64 0
		.amdhsa_float_denorm_mode_32 3
		.amdhsa_float_denorm_mode_16_64 3
		.amdhsa_dx10_clamp 1
		.amdhsa_ieee_mode 1
		.amdhsa_fp16_overflow 0
		.amdhsa_tg_split 0
		.amdhsa_exception_fp_ieee_invalid_op 0
		.amdhsa_exception_fp_denorm_src 0
		.amdhsa_exception_fp_ieee_div_zero 0
		.amdhsa_exception_fp_ieee_overflow 0
		.amdhsa_exception_fp_ieee_underflow 0
		.amdhsa_exception_fp_ieee_inexact 0
		.amdhsa_exception_int_div_zero 0
	.end_amdhsa_kernel

; __global__ __launch_bounds__(512, 2) void fwd_megakernel(Params p) {
.Lfunc_end0:
	.size	_Z14fwd_megakernel6Params, .Lfunc_end0-_Z14fwd_megakernel6Params
	.set _Z14fwd_megakernel6Params.num_vgpr, 244
	.set _Z14fwd_megakernel6Params.num_agpr, 0
	.set _Z14fwd_megakernel6Params.numbered_sgpr, 98
	.set _Z14fwd_megakernel6Params.num_named_barrier, 0
	.set _Z14fwd_megakernel6Params.private_seg_size, 0
	.set _Z14fwd_megakernel6Params.uses_vcc, 1
	.set _Z14fwd_megakernel6Params.uses_flat_scratch, 0
	.set _Z14fwd_megakernel6Params.has_dyn_sized_stack, 0
	.set _Z14fwd_megakernel6Params.has_recursion, 0
	.set _Z14fwd_megakernel6Params.has_indirect_call, 0

; __global__ __launch_bounds__(512, 2) void fwd_megakernel(Params p) {
amdhsa.kernels:
  - .agpr_count:     0
    .args:
      - .offset:         0
        .size:           168
        .value_kind:     by_value
      - .offset:         168
        .size:           4
        .value_kind:     hidden_block_count_x
      - .offset:         172
        .size:           4
        .value_kind:     hidden_block_count_y
      - .offset:         176
        .size:           4
        .value_kind:     hidden_block_count_z
      - .offset:         180
        .size:           2
        .value_kind:     hidden_group_size_x
      - .offset:         182
        .size:           2
        .value_kind:     hidden_group_size_y
      - .offset:         184
        .size:           2
        .value_kind:     hidden_group_size_z
      - .offset:         186
        .size:           2
        .value_kind:     hidden_remainder_x
      - .offset:         188
        .size:           2
        .value_kind:     hidden_remainder_y
      - .offset:         190
        .size:           2
        .value_kind:     hidden_remainder_z
      - .offset:         208
        .size:           8
        .value_kind:     hidden_global_offset_x
      - .offset:         216
        .size:           8
        .value_kind:     hidden_global_offset_y
      - .offset:         224
        .size:           8
        .value_kind:     hidden_global_offset_z
      - .offset:         232
        .size:           2
        .value_kind:     hidden_grid_dims
      - .offset:         256
        .size:           8
        .value_kind:     hidden_multigrid_sync_arg
      - .offset:         288
        .size:           4
        .value_kind:     hidden_dynamic_lds_size
    .group_segment_fixed_size: 16
    .kernarg_segment_align: 8
    .kernarg_segment_size: 424
    .language:       OpenCL C
    .language_version:
      - 2
      - 0
    .max_flat_workgroup_size: 512
    .name:           _Z14fwd_megakernel6Params
    .private_segment_fixed_size: 0
    .sgpr_count:     108
    .sgpr_spill_count: 9
    .symbol:         _Z14fwd_megakernel6Params.kd
    .uniform_work_group_size: 1
    .uses_dynamic_stack: false
    .vgpr_count:     244
    .vgpr_spill_count: 0
    .wavefront_size: 64
